# attention loop DMA with running per-lane source pointers: K and V tile loads carry no address arithmetic and are both issued right behind the opening K-fragment reads of each half-step (old mid-half-s
# baseline (speedup 1.0000x reference)
; #define SBAR() __builtin_amdgcn_sched_barrier(0)
; __device__ __forceinline__ int v_st(int k, int c) { const int kk = (k & ~0xC) | ((k & 4) << 1) | ((k & 8) >> 1); return ((kk >> 3) * 4 + (c >> 5)) * 512 + ((kk & 7) * 32 + (c & 31)) * 2; }
; __device__ __forceinline__ int v_rd_base(int lane) { return ((lane & 3) << 3) | (((lane >> 2) & 3) << 6) | (((lane >> 4) & 1) << 5) | (((lane >> 5) & 1) << 8); }
; #define VMW() asm volatile("s_waitcnt vmcnt(0)" ::: "memory")
; #define SLOAD_H(Kp, Vp, k0) do { S.st_v0 = load8(ROW(Vp, k0, sr)); S.st_v1 = load8(ROW(Vp, k0, 32 + sr));              \
;                          S.st_k0 = load8(ROW(Kp, k0, sr)); S.st_k1 = load8(ROW(Kp, k0, 32 + sr)); } while (0)
; #define SWRITE_HV(bf) do { *(bf16x8*)(V_lds + (bf) * SHM_V + vst0) = S.st_v0; *(bf16x8*)(V_lds + (bf) * SHM_V + vst1) = S.st_v1; } while (0)
; #define SWRITE_H(bf) do { SWRITE_HV(bf); SWRITE_HK(bf); } while (0)
; #define MASKT(P0_, P1_, t) do { const int kb_ = KBASE(t); if (kb_ + KVBLK - 1 > qlo) mask_tile(P0_, P1_, qm - kb_, (unsigned)W); } while (0)
; __device__ __forceinline__ void moba_block(const BlockRef& cur, const BlockRef& nxt, char* lds, Seam& S) {
;     ...
;     const int NT = (cur.qb + 1) * 4;
;     constexpr int W = 0x40000000;
;     const int qlo = cur.P0 + wid * QBLK, qm = qlo + r32 - 4 * hi;
;     char* V_lds = lds; char* K_lds = lds + 2 * SHM_V;
;     float* ws = (float*)(lds + 2 * SHM_V + 2 * SHM_K) + wid * 64; float* li_l = ws, * al_l = ws + 32;
;     float m_reg = -1e30f, l_reg = 0; f32x16 o[4] = {};
;     const int sr = tid >> 4, sc = (tid & 15) * 8, vst0 = v_st(sr, sc), vst1 = v_st(32 + sr, sc), kws = KSWZ(sr, sc * 2);
;     const int vb0 = (int)(uintptr_t)V_lds + v_rd_base(lane);
;     const bf16* Kh = cur.K; const bf16* Vh = cur.V;
;     const int qb = cur.qb;
;     const unsigned sel = gate_select(S.qr, lds, qb, r32, hi);
;     ...
;     constexpr int NQL = 8;
;     ...
;     f32x16 pA0, pA1, pB0, pB1; float mnA, mnB, alA, alB; bf16x8 pa0, pa1, pa2, pa3;
;     SWRITE_HV(0); SBAR();
;     if (NT > 1) { SLOAD_H(Kh, Vh, KBASE(1)); }
;     SBAR(); qkt<0>(pA0, pA1, K_lds, r32, hi, S.qr);
;     MASKT(pA0, pA1, 0); partialSM(pA0, pA1, m_reg, mnA, alA, RSEL(0));
;     if (NT > 1) { VMW(); SWRITE_H(1); }
;     __syncthreads();
.LBB0_88:
	s_and_b32 s0, s3, 0x3fffffc0
	v_and_b32_e32 v51, 63, v183
	s_lshl_b32 s0, s0, 2
	s_lshl_b32 s2, s44, 2
	s_add_i32 s0, s0, 0
	v_lshlrev_b32_e32 v52, 8, v166
	v_and_b32_e32 v53, 0x70, v183
	v_lshlrev_b32_e32 v54, 4, v51
	s_xor_b64 s[10:11], s[10:11], -1
	s_add_i32 s2, s2, 4
	s_add_i32 s7, s0, 0x10000
	v_bitop3_b32 v53, v98, v52, v53 bitop3:0xde
	v_lshlrev_b32_e32 v52, 3, v51
	v_and_b32_e32 v54, 0xc0, v54
	v_lshlrev_b32_e32 v55, 1, v51
	v_and_or_b32 v54, v52, 24, v54
	v_and_b32_e32 v55, 32, v55
	v_and_b32_e32 v52, 0x100, v52
	s_cmp_lg_u32 0, -1
	v_or3_b32 v52, v54, v55, v52
	s_cselect_b32 s0, 0, 0
	v_add_u32_e32 v185, s0, v52
	v_and_b32_e32 v52, 1, v165
	v_cmp_eq_u32_e32 vcc, 1, v52
	v_max_f32_e32 v52, v19, v19
	v_max_f32_e32 v54, v18, v18
	v_max_f32_e32 v52, v54, v52
	v_max3_f32 v52, v52, v20, v21
	v_max3_f32 v52, v52, v22, v23
	v_max3_f32 v52, v52, v24, v25
	v_max3_f32 v52, v52, v26, v27
	v_max3_f32 v52, v52, v28, v29
	v_max3_f32 v52, v52, v30, v31
	v_max3_f32 v52, v52, v32, v33
	v_max3_f32 v52, v52, v2, v3
	v_max3_f32 v52, v52, v4, v5
	v_max3_f32 v52, v52, v6, v7
	v_max3_f32 v52, v52, v8, v9
	v_max3_f32 v52, v52, v10, v11
	s_cmp_lt_i32 s44, 1
	v_max3_f32 v52, v52, v12, v13
	s_cselect_b64 s[0:1], -1, 0
	v_max3_f32 v52, v52, v14, v15
	v_max3_f32 v52, v52, v16, v17
	s_or_b64 vcc, s[0:1], vcc
	v_cndmask_b32_e32 v52, v220, v52, vcc
	v_mov_b32_e32 v54, v52
	s_nop 1
	v_permlane32_swap_b32_e32 v52, v54
	v_max_f32_e32 v54, v54, v54
	v_max_f32_e32 v52, v52, v52
	v_max_f32_e32 v52, v52, v54
	v_add_f32_e32 v54, 0x7149f2ca, v52
	v_mul_f32_e32 v54, 0x3db504f3, v54
	v_max_f32_e32 v52, 0xf149f2ca, v52
	v_cmp_ge_f32_e64 s[38:39], s91, v54
	v_sub_f32_e32 v54, 0xf149f2ca, v52
	v_mul_f32_e32 v54, 0x3e0293ee, v54
	s_cmp_eq_u64 s[38:39], exec
	v_exp_f32_e32 v54, v54
	s_cselect_b64 s[38:39], -1, 0
	v_mov_b32_e32 v55, 0xf149f2ca
	v_cndmask_b32_e64 v198, v52, v55, s[38:39]
	v_mul_f32_e32 v52, 0xbe0293ee, v198
	v_cndmask_b32_e32 v52, v220, v52, vcc
	v_cndmask_b32_e64 v196, v54, 1.0, s[38:39]
	v_mov_b32_e32 v54, v52
	v_fmamk_f32 v18, v18, 0x3e0293ee, v52
	v_fmamk_f32 v19, v19, 0x3e0293ee, v52
	v_fmamk_f32 v20, v20, 0x3e0293ee, v52
	v_fmamk_f32 v21, v21, 0x3e0293ee, v52
	v_fmamk_f32 v22, v22, 0x3e0293ee, v52
	v_fmamk_f32 v23, v23, 0x3e0293ee, v52
	v_fmamk_f32 v24, v24, 0x3e0293ee, v52
	v_fmamk_f32 v25, v25, 0x3e0293ee, v52
	v_fmamk_f32 v26, v26, 0x3e0293ee, v52
	v_fmamk_f32 v27, v27, 0x3e0293ee, v52
	v_fmamk_f32 v28, v28, 0x3e0293ee, v52
	v_fmamk_f32 v29, v29, 0x3e0293ee, v52
	v_fmamk_f32 v30, v30, 0x3e0293ee, v52
	v_fmamk_f32 v31, v31, 0x3e0293ee, v52
	v_fmamk_f32 v32, v32, 0x3e0293ee, v52
	v_fmac_f32_e32 v54, 0x3e0293ee, v33
	s_add_i32 s0, s6, 0xbfffff45
	v_pk_fma_f32 v[178:179], v[2:3], s[20:21], v[52:53] op_sel_hi:[1,0,0]
	v_exp_f32_e32 v231, v18
	v_exp_f32_e32 v233, v19
	v_exp_f32_e32 v229, v20
	v_exp_f32_e32 v232, v21
	v_exp_f32_e32 v228, v22
	v_exp_f32_e32 v230, v23
	v_exp_f32_e32 v226, v24
	v_exp_f32_e32 v227, v25
	v_exp_f32_e32 v223, v26
	v_exp_f32_e32 v225, v27
	v_exp_f32_e32 v209, v28
	v_exp_f32_e32 v224, v29
	v_exp_f32_e32 v206, v30
	v_exp_f32_e32 v208, v31
	v_exp_f32_e32 v205, v32
	v_exp_f32_e32 v207, v54
	v_add_u32_e32 v2, s0, v184
	s_waitcnt vmcnt(0)
	v_add_u32_e32 v188, 0, v53
	v_cmp_gt_u32_e64 s[38:39], 32, v51
	v_lshl_add_u32 v186, v50, 2, s7
	v_sub_u32_e32 v197, v2, v50
	v_mov_b32_e32 v50, v99
	v_mov_b32_e32 v51, v99
	v_pk_fma_f32 v[154:155], v[16:17], s[20:21], v[52:53] op_sel_hi:[1,0,0]
	v_pk_fma_f32 v[160:161], v[14:15], s[20:21], v[52:53] op_sel_hi:[1,0,0]
	v_pk_fma_f32 v[180:181], v[12:13], s[20:21], v[52:53] op_sel_hi:[1,0,0]
	v_pk_fma_f32 v[152:153], v[10:11], s[20:21], v[52:53] op_sel_hi:[1,0,0]
	v_pk_fma_f32 v[156:157], v[8:9], s[20:21], v[52:53] op_sel_hi:[1,0,0]
	v_pk_fma_f32 v[158:159], v[6:7], s[20:21], v[52:53] op_sel_hi:[1,0,0]
	v_pk_fma_f32 v[162:163], v[4:5], s[20:21], v[52:53] op_sel_hi:[1,0,0]
	s_waitcnt vmcnt(3)
	ds_write_b128 v191, v[34:37] offset:16384
	s_waitcnt vmcnt(2)
	ds_write_b128 v192, v[38:41] offset:16384
	s_waitcnt vmcnt(1)
	ds_write_b128 v188, v[42:45] offset:49152
	s_waitcnt vmcnt(0)
	ds_write_b128 v188, v[46:49] offset:57344
	v_mov_b32_e32 v52, v99
	v_mov_b32_e32 v53, v99
	v_mov_b32_e32 v54, v99
	v_mov_b32_e32 v55, v99
	v_mov_b32_e32 v56, v99
	v_mov_b32_e32 v57, v99
	v_mov_b32_e32 v58, v99
	v_mov_b32_e32 v59, v99
	v_mov_b32_e32 v60, v99
	v_mov_b32_e32 v61, v99
	v_mov_b32_e32 v62, v99
	v_mov_b32_e32 v63, v99
	v_mov_b32_e32 v64, v99
	v_mov_b32_e32 v65, v99
	v_mov_b64_e32 v[34:35], v[50:51]
	v_mov_b64_e32 v[18:19], v[50:51]
	v_mov_b64_e32 v[2:3], v[50:51]
	s_mov_b32 s3, 3
	v_lshl_add_u64 v[170:171], s[22:23], 0, v[98:99]
	v_lshl_add_u64 v[176:177], s[30:31], 0, v[98:99]
	v_lshl_add_u32 v187, v184, 2, s7
	v_mov_b32_e32 v189, 0
	s_movk_i32 s7, 0x7f
	v_mov_b64_e32 v[36:37], v[52:53]
	v_mov_b64_e32 v[38:39], v[54:55]
	v_mov_b64_e32 v[40:41], v[56:57]
	v_mov_b64_e32 v[42:43], v[58:59]
	v_mov_b64_e32 v[44:45], v[60:61]
	v_mov_b64_e32 v[46:47], v[62:63]
	v_mov_b64_e32 v[48:49], v[64:65]
	v_mov_b64_e32 v[20:21], v[52:53]
	v_mov_b64_e32 v[22:23], v[54:55]
	v_mov_b64_e32 v[24:25], v[56:57]
	v_mov_b64_e32 v[26:27], v[58:59]
	v_mov_b64_e32 v[28:29], v[60:61]
	v_mov_b64_e32 v[30:31], v[62:63]
	v_mov_b64_e32 v[32:33], v[64:65]
	v_mov_b64_e32 v[4:5], v[52:53]
	v_mov_b64_e32 v[6:7], v[54:55]
	v_mov_b64_e32 v[8:9], v[56:57]
	v_mov_b64_e32 v[10:11], v[58:59]
	v_mov_b64_e32 v[12:13], v[60:61]
	v_mov_b64_e32 v[14:15], v[62:63]
	v_mov_b64_e32 v[16:17], v[64:65]
	s_mov_b32 s100, 0
	v_readfirstlane_b32 s32, v0
	s_lshr_b32 s32, s32, 6
	s_lshl_b32 s32, s32, 10
	s_add_i32 s32, s32, 0x8000
	v_lshrrev_b32_e32 v236, 4, v0
	v_and_b32_e32 v237, 7, v236
	v_and_b32_e32 v240, 15, v0
	v_xor_b32_e32 v237, v237, v240
	v_sub_u32_e32 v237, v237, v240
	v_lshlrev_b32_e32 v237, 4, v237
	v_lshlrev_b32_e32 v236, 8, v236
	v_add_u32_e32 v236, 0x8000, v236
	v_add_u32_e32 v240, v236, v237
	v_mov_b32_e32 v241, 0
	v_lshl_add_u64 v[244:245], v[176:177], 0, v[240:241]
	v_add_u32_e32 v240, 0x2000, v240
	v_lshl_add_u64 v[246:247], v[176:177], 0, v[240:241]
	v_lshrrev_b32_e32 v236, 6, v0
	v_bfe_u32 v237, v0, 2, 3
	v_lshrrev_b32_e32 v240, 1, v236
	v_lshlrev_b32_e32 v240, 4, v240
	v_and_b32_e32 v250, 4, v237
	v_lshl_or_b32 v240, v250, 1, v240
	v_and_b32_e32 v250, 1, v236
	v_lshl_or_b32 v240, v250, 2, v240
	v_and_b32_e32 v250, 3, v237
	v_or_b32_e32 v240, v240, v250
	v_lshlrev_b32_e32 v240, 8, v240
	v_bfe_u32 v250, v0, 5, 1
	v_lshl_or_b32 v240, v250, 6, v240
	v_and_b32_e32 v250, 3, v0
	v_lshl_or_b32 v240, v250, 4, v240
	v_and_b32_e32 v250, 15, v0
	v_lshlrev_b32_e32 v250, 4, v250
	v_sub_u32_e32 v240, v240, v250
	v_add_u32_e32 v240, 0x8000, v240
	v_lshl_add_u64 v[248:249], v[170:171], 0, v[240:241]
	v_mov_b32_e32 v250, 0x4000
	v_mov_b32_e32 v251, 0
	s_waitcnt lgkmcnt(0)
	s_barrier
; __device__ __forceinline__ void finishSM(f32x16& p0, f32x16& p1, float alpha, float& l_reg, bf16x8& pa0, bf16x8& pa1, bf16x8& pa2, bf16x8& pa3) {
;     for (int r = 0; r < 16; ++r) p1[r] = __builtin_amdgcn_exp2f(p1[r]);
;     float ps = 0; for (int r = 0; r < 16; ++r) ps += p0[r]; for (int r = 0; r < 16; ++r) ps += p1[r];
;     { auto rr = __builtin_amdgcn_permlane32_swap(__float_as_uint(ps), __float_as_uint(ps), false, false);
;       ps = __uint_as_float(rr[0]) + __uint_as_float(rr[1]); }
;     l_reg = l_reg * alpha + ps;
;     ...
;     PK4(p0, 0, pa0); PK4(p0, 8, pa1); PK4(p1, 0, pa2); PK4(p1, 8, pa3);
;     ...
; }
; template <int KB>
; __device__ __forceinline__ void qkt(f32x16& p0, f32x16& p1, const char* K_lds, int r32, int hi, const bf16x8* qr) {
;     p0 = f32x16{}; p1 = f32x16{};
;     const char* kb[4];
; #pragma unroll
;     for (int dd = 0; dd < 4; ++dd) kb[dd] = K_lds + KB * SHM_K + KSWZ(r32, (dd * 16 + hi * 8) * 2);
; #pragma unroll
;     for (int d0 = 0; d0 < 8; ++d0) { const char* a = kb[d0 & 3] + (d0 >> 2) * 128;
;         bf16x8 b0 = *reinterpret_cast<const bf16x8*>(a);
;         bf16x8 b1 = *reinterpret_cast<const bf16x8*>(a + 32 * 256);
;         p0 = __builtin_amdgcn_mfma_f32_32x32x16_bf16(b0, qr[d0], p0, 0, 0, 0);
;         p1 = __builtin_amdgcn_mfma_f32_32x32x16_bf16(b1, qr[d0], p1, 0, 0, 0); }
; }
.LBB0_89:
	ds_read_b128 v[66:69], v169 offset:49152
	ds_read_b128 v[70:73], v169 offset:57344
	ds_read_b128 v[100:103], v193 offset:49152
	ds_read_b128 v[136:139], v193 offset:57344
	s_cmp_eq_u32 s100, 0
	s_cbranch_scc1 .Lmy_hs1_nov
	s_lshl_b32 m0, s32, 1
	s_sub_i32 m0, m0, 0xc000
	s_nop 0
	global_load_lds_dwordx4 v[248:249], off
	s_add_i32 m0, m0, 896
	s_nop 0
	global_load_lds_dwordx4 v[248:249], off offset:128
	v_lshl_add_u64 v[248:249], v[248:249], 0, v[250:251]
.Lmy_hs1_nov:
	s_mov_b32 s100, 0
	s_mov_b32 m0, s32
	s_nop 0
	global_load_lds_dwordx4 v[244:245], off
	s_add_i32 m0, s32, 0x2000
	s_nop 0
	global_load_lds_dwordx4 v[246:247], off
	v_lshl_add_u64 v[244:245], v[244:245], 0, v[250:251]
	v_lshl_add_u64 v[246:247], v[246:247], 0, v[250:251]
	v_add_f32_e32 v148, 0, v231
	v_add_f32_e32 v148, v233, v148
	v_add_f32_e32 v148, v229, v148
	v_add_f32_e32 v148, v232, v148
	v_add_f32_e32 v148, v228, v148
	v_add_f32_e32 v148, v230, v148
	v_add_f32_e32 v148, v226, v148
	v_add_f32_e32 v148, v227, v148
	v_add_f32_e32 v148, v223, v148
	v_add_f32_e32 v148, v225, v148
	v_add_f32_e32 v148, v209, v148
	v_add_f32_e32 v148, v224, v148
	v_add_f32_e32 v148, v206, v148
	v_add_f32_e32 v148, v208, v148
	v_add_f32_e32 v148, v205, v148
	v_add_f32_e32 v148, v207, v148
	v_exp_f32_e32 v140, v152
	v_exp_f32_e32 v141, v153
	v_exp_f32_e32 v142, v180
	v_exp_f32_e32 v143, v181
	s_waitcnt lgkmcnt(3)
	v_mfma_f32_32x32x16_bf16 v[82:97], v[66:69], v[132:135], 0
	v_exp_f32_e32 v144, v160
	v_exp_f32_e32 v145, v161
	v_exp_f32_e32 v146, v154
	v_exp_f32_e32 v147, v155
	s_waitcnt lgkmcnt(2)
	v_mfma_f32_32x32x16_bf16 v[66:81], v[70:73], v[132:135], 0
	v_exp_f32_e32 v178, v178
	v_exp_f32_e32 v179, v179
	v_exp_f32_e32 v162, v162
	v_exp_f32_e32 v163, v163
	s_waitcnt lgkmcnt(1)
	v_mfma_f32_32x32x16_bf16 v[82:97], v[100:103], v[128:131], v[82:97]
	v_add_f32_e32 v148, v178, v148
	v_add_f32_e32 v148, v179, v148
	v_add_f32_e32 v148, v162, v148
	v_exp_f32_e32 v158, v158
	s_waitcnt lgkmcnt(0)
	v_mfma_f32_32x32x16_bf16 v[66:81], v[136:139], v[128:131], v[66:81]
	v_exp_f32_e32 v159, v159
	v_exp_f32_e32 v156, v156
	v_exp_f32_e32 v157, v157
	v_add_f32_e32 v148, v163, v148
	ds_read_b128 v[100:103], v194 offset:49152
	ds_read_b128 v[136:139], v194 offset:57344
	s_waitcnt lgkmcnt(1)
	v_mfma_f32_32x32x16_bf16 v[82:97], v[100:103], v[124:127], v[82:97]
	v_add_f32_e32 v148, v158, v148
	v_add_f32_e32 v148, v159, v148
	v_add_f32_e32 v148, v156, v148
	v_add_f32_e32 v148, v157, v148
	s_waitcnt lgkmcnt(0)
	v_mfma_f32_32x32x16_bf16 v[66:81], v[136:139], v[124:127], v[66:81]
	v_add_f32_e32 v148, v140, v148
	v_add_f32_e32 v148, v141, v148
	v_add_f32_e32 v148, v142, v148
	v_add_f32_e32 v148, v143, v148
	ds_read_b128 v[100:103], v195 offset:49152
	ds_read_b128 v[136:139], v195 offset:57344
	s_waitcnt lgkmcnt(1)
	v_mfma_f32_32x32x16_bf16 v[82:97], v[100:103], v[120:123], v[82:97]
	v_add_f32_e32 v148, v144, v148
	v_add_f32_e32 v148, v145, v148
	v_add_f32_e32 v148, v146, v148
	v_add_f32_e32 v199, v147, v148
	s_waitcnt lgkmcnt(0)
	v_mfma_f32_32x32x16_bf16 v[66:81], v[136:139], v[120:123], v[66:81]
	v_mov_b32_e32 v200, v199
	s_nop 1
	v_permlane32_swap_b32_e32 v199, v200
	v_cvt_pk_bf16_f32 v148, v231, v233
	v_cvt_pk_bf16_f32 v149, v229, v232
	v_cvt_pk_bf16_f32 v150, v228, v230
	ds_read_b128 v[100:103], v169 offset:49280
	ds_read_b128 v[136:139], v169 offset:57472
	s_waitcnt lgkmcnt(1)
	v_mfma_f32_32x32x16_bf16 v[82:97], v[100:103], v[116:119], v[82:97]
	v_cvt_pk_bf16_f32 v151, v226, v227
	v_cvt_pk_bf16_f32 v152, v223, v225
	v_cvt_pk_bf16_f32 v153, v209, v224
	s_waitcnt lgkmcnt(0)
	v_mfma_f32_32x32x16_bf16 v[66:81], v[136:139], v[116:119], v[66:81]
	v_cvt_pk_bf16_f32 v154, v206, v208
	v_cvt_pk_bf16_f32 v155, v205, v207
	v_cvt_pk_bf16_f32 v158, v158, v159
	ds_read_b128 v[100:103], v193 offset:49280
	ds_read_b128 v[136:139], v193 offset:57472
	s_waitcnt lgkmcnt(1)
	v_mfma_f32_32x32x16_bf16 v[82:97], v[100:103], v[112:115], v[82:97]
	v_cvt_pk_bf16_f32 v159, v156, v157
	v_cvt_pk_bf16_f32 v156, v178, v179
	v_cvt_pk_bf16_f32 v157, v162, v163
	s_waitcnt lgkmcnt(0)
	v_mfma_f32_32x32x16_bf16 v[66:81], v[136:139], v[112:115], v[66:81]
	v_cvt_pk_bf16_f32 v160, v140, v141
	v_cvt_pk_bf16_f32 v161, v142, v143
	v_cvt_pk_bf16_f32 v162, v144, v145
	ds_read_b128 v[100:103], v194 offset:49280
	ds_read_b128 v[136:139], v194 offset:57472
	s_waitcnt lgkmcnt(1)
	v_mfma_f32_32x32x16_bf16 v[82:97], v[100:103], v[108:111], v[82:97]
	v_cvt_pk_bf16_f32 v163, v146, v147
	s_nop 0
	v_permlane32_swap_b32_e32 v148, v150
	v_permlane32_swap_b32_e32 v149, v151
	s_waitcnt lgkmcnt(0)
	v_mfma_f32_32x32x16_bf16 v[66:81], v[136:139], v[108:111], v[66:81]
	v_permlane32_swap_b32_e32 v152, v154
	v_permlane32_swap_b32_e32 v153, v155
	v_permlane32_swap_b32_e32 v156, v158
	ds_read_b128 v[100:103], v195 offset:49280
	ds_read_b128 v[136:139], v195 offset:57472
	ds_read_b64_tr_b16 v[172:173], v185 offset:0
	ds_read_b64_tr_b16 v[174:175], v185 offset:0x800
	ds_read_b64_tr_b16 v[202:203], v185 offset:0x1000
	ds_read_b64_tr_b16 v[204:205], v185 offset:0x1800
	ds_read_b64_tr_b16 v[206:207], v185 offset:0x2000
	ds_read_b64_tr_b16 v[208:209], v185 offset:0x2800
	ds_read_b64_tr_b16 v[224:225], v185 offset:0x3000
	ds_read_b64_tr_b16 v[226:227], v185 offset:0x3800
	s_waitcnt lgkmcnt(9)
	v_mfma_f32_32x32x16_bf16 v[82:97], v[100:103], v[104:107], v[82:97]
	v_permlane32_swap_b32_e32 v157, v159
	v_permlane32_swap_b32_e32 v160, v162
	v_permlane32_swap_b32_e32 v161, v163
	s_waitcnt lgkmcnt(8)
	v_mfma_f32_32x32x16_bf16 v[66:81], v[136:139], v[104:107], v[66:81]
	s_waitcnt lgkmcnt(0)
; __device__ __forceinline__ void mask_tile(f32x16& p0, f32x16& p1, int dq, unsigned W) {
;     const float NEG = -__builtin_inff();
; #pragma unroll
;     for (int r = 0; r < 16; ++r) {
;         const int c = (r & 3) + 8 * (r >> 2);
;         if ((unsigned)(dq - c) >= W) p0[r] = NEG;
;         if ((unsigned)(dq - c - 32) >= W) p1[r] = NEG;
;     }
; }
; template <int VB>
; __device__ __forceinline__ void pv_tile(f32x16* o, int vb0, bf16x8 pa0, bf16x8 pa1, bf16x8 pa2, bf16x8 pa3) {
;     ...
;     PV_D0(0); PV_D0(1); PV_D0(2); PV_D0(3);
	s_nop 0
	v_mfma_f32_32x32x16_bf16 v[50:65], v[148:151], v[172:175], v[50:65]
	ds_read_b64_tr_b16 v[172:173], v185 offset:0x200
	ds_read_b64_tr_b16 v[174:175], v185 offset:0xa00
	v_mfma_f32_32x32x16_bf16 v[50:65], v[152:155], v[202:205], v[50:65]
	ds_read_b64_tr_b16 v[202:203], v185 offset:0x1200
	ds_read_b64_tr_b16 v[204:205], v185 offset:0x1a00
	v_mfma_f32_32x32x16_bf16 v[50:65], v[156:159], v[206:209], v[50:65]
	ds_read_b64_tr_b16 v[206:207], v185 offset:0x2200
	ds_read_b64_tr_b16 v[208:209], v185 offset:0x2a00
	v_mfma_f32_32x32x16_bf16 v[50:65], v[160:163], v[224:227], v[50:65]
	ds_read_b64_tr_b16 v[224:225], v185 offset:0x3200
	ds_read_b64_tr_b16 v[226:227], v185 offset:0x3a00
	s_waitcnt lgkmcnt(0)
	v_mfma_f32_32x32x16_bf16 v[34:49], v[148:151], v[172:175], v[34:49]
	ds_read_b64_tr_b16 v[172:173], v185 offset:0x400
	ds_read_b64_tr_b16 v[174:175], v185 offset:0xc00
	v_mfma_f32_32x32x16_bf16 v[34:49], v[152:155], v[202:205], v[34:49]
	ds_read_b64_tr_b16 v[202:203], v185 offset:0x1400
	ds_read_b64_tr_b16 v[204:205], v185 offset:0x1c00
	v_mfma_f32_32x32x16_bf16 v[34:49], v[156:159], v[206:209], v[34:49]
	ds_read_b64_tr_b16 v[206:207], v185 offset:0x2400
	ds_read_b64_tr_b16 v[208:209], v185 offset:0x2c00
	v_mfma_f32_32x32x16_bf16 v[34:49], v[160:163], v[224:227], v[34:49]
	ds_read_b64_tr_b16 v[224:225], v185 offset:0x3400
	ds_read_b64_tr_b16 v[226:227], v185 offset:0x3c00
	s_waitcnt lgkmcnt(0)
	v_mfma_f32_32x32x16_bf16 v[18:33], v[148:151], v[172:175], v[18:33]
	ds_read_b64_tr_b16 v[172:173], v185 offset:0x600
	ds_read_b64_tr_b16 v[174:175], v185 offset:0xe00
	v_mfma_f32_32x32x16_bf16 v[18:33], v[152:155], v[202:205], v[18:33]
	ds_read_b64_tr_b16 v[202:203], v185 offset:0x1600
	ds_read_b64_tr_b16 v[204:205], v185 offset:0x1e00
	v_mfma_f32_32x32x16_bf16 v[18:33], v[156:159], v[206:209], v[18:33]
	ds_read_b64_tr_b16 v[206:207], v185 offset:0x2600
	ds_read_b64_tr_b16 v[208:209], v185 offset:0x2e00
	v_mfma_f32_32x32x16_bf16 v[18:33], v[160:163], v[224:227], v[18:33]
	ds_read_b64_tr_b16 v[224:225], v185 offset:0x3600
	ds_read_b64_tr_b16 v[226:227], v185 offset:0x3e00
	s_waitcnt lgkmcnt(0)
	v_mfma_f32_32x32x16_bf16 v[2:17], v[148:151], v[172:175], v[2:17]
	s_cmp_le_i32 s7, s6
	v_mfma_f32_32x32x16_bf16 v[2:17], v[152:155], v[202:205], v[2:17]
	v_mfma_f32_32x32x16_bf16 v[2:17], v[156:159], v[206:209], v[2:17]
	v_mfma_f32_32x32x16_bf16 v[2:17], v[160:163], v[224:227], v[2:17]
	s_cbranch_scc1 .LBB0_91
	v_add_u32_e32 v148, 0x4000007b, v197
	v_cmp_gt_u32_e32 vcc, 2.0, v148
	v_add_u32_e32 v148, 0x5b, v197
	s_nop 0
	v_cndmask_b32_e32 v82, v220, v82, vcc
	v_cmp_lt_u32_e32 vcc, s33, v148
	v_add_u32_e32 v148, 0x7a, v197
	s_nop 0
	v_cndmask_b32_e32 v66, v220, v66, vcc
	v_cmp_lt_u32_e32 vcc, s33, v148
	v_add_u32_e32 v148, 0x5a, v197
	s_nop 0
	v_cndmask_b32_e32 v83, v220, v83, vcc
	v_cmp_lt_u32_e32 vcc, s33, v148
	v_add_u32_e32 v148, 0x79, v197
	s_nop 0
	v_cndmask_b32_e32 v67, v220, v67, vcc
	v_cmp_lt_u32_e32 vcc, s33, v148
	v_add_u32_e32 v148, 0x59, v197
	s_nop 0
	v_cndmask_b32_e32 v84, v220, v84, vcc
	v_cmp_lt_u32_e32 vcc, s33, v148
	v_add_u32_e32 v148, 0x78, v197
	s_nop 0
	v_cndmask_b32_e32 v68, v220, v68, vcc
	v_cmp_lt_u32_e32 vcc, s33, v148
	v_add_u32_e32 v148, 0x58, v197
	s_nop 0
	v_cndmask_b32_e32 v85, v220, v85, vcc
	v_cmp_lt_u32_e32 vcc, s33, v148
	v_add_u32_e32 v148, 0x73, v197
	s_nop 0
	v_cndmask_b32_e32 v69, v220, v69, vcc
	v_cmp_lt_u32_e32 vcc, s33, v148
	v_add_u32_e32 v148, 0x53, v197
	s_nop 0
	v_cndmask_b32_e32 v86, v220, v86, vcc
	v_cmp_lt_u32_e32 vcc, s33, v148
	v_add_u32_e32 v148, 0x72, v197
	s_nop 0
	v_cndmask_b32_e32 v70, v220, v70, vcc
	v_cmp_lt_u32_e32 vcc, s33, v148
	v_add_u32_e32 v148, 0x52, v197
	s_nop 0
	v_cndmask_b32_e32 v87, v220, v87, vcc
	v_cmp_lt_u32_e32 vcc, s33, v148
	v_add_u32_e32 v148, 0x71, v197
	s_nop 0
	v_cndmask_b32_e32 v71, v220, v71, vcc
	v_cmp_lt_u32_e32 vcc, s33, v148
	v_add_u32_e32 v148, 0x51, v197
	s_nop 0
	v_cndmask_b32_e32 v88, v220, v88, vcc
	v_cmp_lt_u32_e32 vcc, s33, v148
	v_add_u32_e32 v148, 0x70, v197
	s_nop 0
	v_cndmask_b32_e32 v72, v220, v72, vcc
	v_cmp_lt_u32_e32 vcc, s33, v148
	v_add_u32_e32 v148, 0x50, v197
	s_nop 0
	v_cndmask_b32_e32 v89, v220, v89, vcc
	v_cmp_lt_u32_e32 vcc, s33, v148
	v_add_u32_e32 v148, 0x6b, v197
	s_nop 0
	v_cndmask_b32_e32 v73, v220, v73, vcc
	v_cmp_lt_u32_e32 vcc, s33, v148
	v_add_u32_e32 v148, 0x4b, v197
	s_nop 0
	v_cndmask_b32_e32 v90, v220, v90, vcc
	v_cmp_lt_u32_e32 vcc, s33, v148
	v_add_u32_e32 v148, 0x6a, v197
	s_nop 0
	v_cndmask_b32_e32 v74, v220, v74, vcc
	v_cmp_lt_u32_e32 vcc, s33, v148
	v_add_u32_e32 v148, 0x4a, v197
	s_nop 0
	v_cndmask_b32_e32 v91, v220, v91, vcc
	v_cmp_lt_u32_e32 vcc, s33, v148
	v_add_u32_e32 v148, 0x69, v197
	s_nop 0
	v_cndmask_b32_e32 v75, v220, v75, vcc
	v_cmp_lt_u32_e32 vcc, s33, v148
	v_add_u32_e32 v148, 0x49, v197
	s_nop 0
	v_cndmask_b32_e32 v92, v220, v92, vcc
	v_cmp_lt_u32_e32 vcc, s33, v148
	v_add_u32_e32 v148, 0x68, v197
	s_nop 0
	v_cndmask_b32_e32 v76, v220, v76, vcc
	v_cmp_lt_u32_e32 vcc, s33, v148
	v_add_u32_e32 v148, 0x48, v197
	s_nop 0
	v_cndmask_b32_e32 v93, v220, v93, vcc
	v_cmp_lt_u32_e32 vcc, s33, v148
	v_add_u32_e32 v148, 0x63, v197
	s_nop 0
	v_cndmask_b32_e32 v77, v220, v77, vcc
	v_cmp_lt_u32_e32 vcc, s33, v148
	v_add_u32_e32 v148, 0x43, v197
	s_nop 0
	v_cndmask_b32_e32 v94, v220, v94, vcc
	v_cmp_lt_u32_e32 vcc, s33, v148
	v_add_u32_e32 v148, 0x62, v197
	s_nop 0
	v_cndmask_b32_e32 v78, v220, v78, vcc
	v_cmp_lt_u32_e32 vcc, s33, v148
	v_add_u32_e32 v148, 0x42, v197
	s_nop 0
	v_cndmask_b32_e32 v95, v220, v95, vcc
	v_cmp_lt_u32_e32 vcc, s33, v148
	v_add_u32_e32 v148, 0x61, v197
	s_nop 0
	v_cndmask_b32_e32 v79, v220, v79, vcc
	v_cmp_lt_u32_e32 vcc, s33, v148
	v_add_u32_e32 v148, 0x41, v197
	s_nop 0
	v_cndmask_b32_e32 v96, v220, v96, vcc
	v_cmp_lt_u32_e32 vcc, s33, v148
	v_add_u32_e32 v148, 0x60, v197
	s_nop 0
	v_cndmask_b32_e32 v80, v220, v80, vcc
	v_cmp_lt_u32_e32 vcc, s33, v148
	v_add_u32_e32 v148, 64, v197
	s_nop 0
	v_cndmask_b32_e32 v97, v220, v97, vcc
	v_cmp_lt_u32_e32 vcc, s33, v148
	s_nop 1
	v_cndmask_b32_e32 v81, v220, v81, vcc

; __device__ __forceinline__ void partialSM(f32x16& p0, f32x16& p1, float& m_reg, float& mn, float& alpha, bool rs) {
;     ...
;     if (__builtin_expect(__all((pmax - m_reg) * SCALE <= THR), 1)) { mn = m_reg; alpha = 1.f; }
;     else { mn = fmaxf(m_reg, pmax); alpha = __builtin_amdgcn_exp2f((m_reg - mn) * C2); m_reg = mn; }
;     const float mnL = rs ? -mn * C2 : -__builtin_inff();
;     for (int r = 0; r < 16; ++r) p0[r] = fmaf(p0[r], C2, mnL); for (int r = 0; r < 16; ++r) p1[r] = fmaf(p1[r], C2, mnL);
;     for (int r = 0; r < 16; ++r) p0[r] = __builtin_amdgcn_exp2f(p0[r]);
; }
.LBB0_95:
	v_cndmask_b32_e64 v179, v148, v198, s[42:43]
	v_mul_f32_e32 v148, 0xbe0293ee, v179
	v_cndmask_b32_e64 v180, v220, v148, s[40:41]
	v_fmamk_f32 v82, v82, 0x3e0293ee, v180
	v_fmamk_f32 v83, v83, 0x3e0293ee, v180
	v_fmamk_f32 v84, v84, 0x3e0293ee, v180
	v_fmamk_f32 v85, v85, 0x3e0293ee, v180
	v_fmamk_f32 v86, v86, 0x3e0293ee, v180
	v_fmamk_f32 v87, v87, 0x3e0293ee, v180
	v_fmamk_f32 v88, v88, 0x3e0293ee, v180
	v_fmamk_f32 v89, v89, 0x3e0293ee, v180
	v_fmamk_f32 v90, v90, 0x3e0293ee, v180
	v_fmamk_f32 v91, v91, 0x3e0293ee, v180
	v_fmamk_f32 v92, v92, 0x3e0293ee, v180
	v_fmamk_f32 v93, v93, 0x3e0293ee, v180
	v_fmamk_f32 v94, v94, 0x3e0293ee, v180
	v_fmamk_f32 v95, v95, 0x3e0293ee, v180
	v_fmamk_f32 v96, v96, 0x3e0293ee, v180
	v_fmamk_f32 v97, v97, 0x3e0293ee, v180
	v_exp_f32_e32 v148, v82
	v_exp_f32_e32 v163, v83
	v_exp_f32_e32 v149, v84
	v_exp_f32_e32 v162, v85
	v_exp_f32_e32 v150, v86
	v_exp_f32_e32 v161, v87
	v_exp_f32_e32 v151, v88
	v_exp_f32_e32 v160, v89
	v_exp_f32_e32 v152, v90
	v_exp_f32_e32 v159, v91
	v_exp_f32_e32 v153, v92
	v_exp_f32_e32 v158, v93
	v_exp_f32_e32 v154, v94
	v_exp_f32_e32 v157, v95
	v_exp_f32_e32 v155, v96
	v_exp_f32_e32 v156, v97
	v_fmamk_f32 v203, v73, 0x3e0293ee, v180
	v_fmamk_f32 v204, v74, 0x3e0293ee, v180
	v_fmamk_f32 v208, v66, 0x3e0293ee, v180
	v_fmamk_f32 v209, v67, 0x3e0293ee, v180
	v_fmamk_f32 v223, v68, 0x3e0293ee, v180
	v_fmamk_f32 v224, v69, 0x3e0293ee, v180
	v_fmamk_f32 v225, v70, 0x3e0293ee, v180
	v_fmamk_f32 v198, v71, 0x3e0293ee, v180
	v_fmamk_f32 v201, v72, 0x3e0293ee, v180
	v_fmamk_f32 v205, v75, 0x3e0293ee, v180
	v_fmamk_f32 v206, v76, 0x3e0293ee, v180
	v_fmamk_f32 v207, v77, 0x3e0293ee, v180
	v_fmamk_f32 v181, v78, 0x3e0293ee, v180
	v_fmamk_f32 v226, v79, 0x3e0293ee, v180
	v_fmamk_f32 v227, v80, 0x3e0293ee, v180
	v_fmac_f32_e32 v180, 0x3e0293ee, v81
	s_waitcnt lgkmcnt(0)
	s_barrier
	ds_read_b128 v[66:69], v169 offset:32768
	ds_read_b128 v[70:73], v169 offset:40960
	ds_read_b128 v[172:175], v193 offset:32768
	ds_read_b128 v[228:231], v193 offset:40960
	s_lshl_b32 m0, s32, 1
	s_sub_i32 m0, m0, 0x10000
	s_nop 0
	global_load_lds_dwordx4 v[248:249], off
	s_add_i32 m0, m0, 896
	s_nop 0
	global_load_lds_dwordx4 v[248:249], off offset:128
	v_lshl_add_u64 v[248:249], v[248:249], 0, v[250:251]
	s_cmp_ge_u32 s3, s2
	s_cbranch_scc1 .Lmy_hs2_nok
	s_add_i32 m0, s32, 0x4000
	s_nop 0
	global_load_lds_dwordx4 v[244:245], off
	s_add_i32 m0, s32, 0x6000
	s_nop 0
	global_load_lds_dwordx4 v[246:247], off
	v_lshl_add_u64 v[244:245], v[244:245], 0, v[250:251]
	v_lshl_add_u64 v[246:247], v[246:247], 0, v[250:251]
; __device__ __forceinline__ void finishSM(f32x16& p0, f32x16& p1, float alpha, float& l_reg, bf16x8& pa0, bf16x8& pa1, bf16x8& pa2, bf16x8& pa3) {
;     for (int r = 0; r < 16; ++r) p1[r] = __builtin_amdgcn_exp2f(p1[r]);
;     float ps = 0; for (int r = 0; r < 16; ++r) ps += p0[r]; for (int r = 0; r < 16; ++r) ps += p1[r];
;     { auto rr = __builtin_amdgcn_permlane32_swap(__float_as_uint(ps), __float_as_uint(ps), false, false);
;       ps = __uint_as_float(rr[0]) + __uint_as_float(rr[1]); }
;     l_reg = l_reg * alpha + ps;
;     ...
;     PK4(p0, 0, pa0); PK4(p0, 8, pa1); PK4(p1, 0, pa2); PK4(p1, 8, pa3);
;     ...
; }
; template <int KB>
; __device__ __forceinline__ void qkt(f32x16& p0, f32x16& p1, const char* K_lds, int r32, int hi, const bf16x8* qr) {
;     p0 = f32x16{}; p1 = f32x16{};
;     const char* kb[4];
; #pragma unroll
;     for (int dd = 0; dd < 4; ++dd) kb[dd] = K_lds + KB * SHM_K + KSWZ(r32, (dd * 16 + hi * 8) * 2);
; #pragma unroll
;     for (int d0 = 0; d0 < 8; ++d0) { const char* a = kb[d0 & 3] + (d0 >> 2) * 128;
;         bf16x8 b0 = *reinterpret_cast<const bf16x8*>(a);
;         bf16x8 b1 = *reinterpret_cast<const bf16x8*>(a + 32 * 256);
;         p0 = __builtin_amdgcn_mfma_f32_32x32x16_bf16(b0, qr[d0], p0, 0, 0, 0);
;         p1 = __builtin_amdgcn_mfma_f32_32x32x16_bf16(b1, qr[d0], p1, 0, 0, 0); }
; }
.Lmy_hs2_nok:
	v_exp_f32_e32 v198, v198
	v_exp_f32_e32 v201, v201
	v_exp_f32_e32 v214, v204
	v_exp_f32_e32 v205, v205
	v_exp_f32_e32 v206, v206
	v_exp_f32_e32 v207, v207
	v_exp_f32_e32 v181, v181
	v_exp_f32_e32 v215, v226
	v_exp_f32_e32 v216, v227
	v_exp_f32_e32 v180, v180
	v_exp_f32_e32 v218, v209
	v_exp_f32_e32 v209, v203
	v_add_f32_e32 v203, 0, v148
	v_add_f32_e32 v203, v163, v203
	v_add_f32_e32 v203, v149, v203
	v_add_f32_e32 v203, v162, v203
	v_add_f32_e32 v203, v150, v203
	v_add_f32_e32 v203, v161, v203
	v_add_f32_e32 v203, v151, v203
	v_add_f32_e32 v203, v160, v203
	s_waitcnt lgkmcnt(3)
	v_mfma_f32_32x32x16_bf16 v[82:97], v[66:69], v[132:135], 0
	v_add_f32_e32 v203, v152, v203
	v_add_f32_e32 v203, v159, v203
	v_add_f32_e32 v203, v153, v203
	v_add_f32_e32 v203, v158, v203
	s_waitcnt lgkmcnt(2)
	v_mfma_f32_32x32x16_bf16 v[66:81], v[70:73], v[132:135], 0
	v_exp_f32_e32 v217, v208
	v_add_f32_e32 v203, v154, v203
	v_add_f32_e32 v203, v157, v203
	v_exp_f32_e32 v219, v223
	s_waitcnt lgkmcnt(1)
	v_mfma_f32_32x32x16_bf16 v[82:97], v[172:175], v[128:131], v[82:97]
	v_add_f32_e32 v203, v155, v203
	v_exp_f32_e32 v222, v224
	v_add_f32_e32 v203, v156, v203
	v_exp_f32_e32 v208, v225
	s_waitcnt lgkmcnt(0)
	v_mfma_f32_32x32x16_bf16 v[66:81], v[228:231], v[128:131], v[66:81]
	v_add_f32_e32 v203, v217, v203
	v_add_f32_e32 v203, v218, v203
	v_add_f32_e32 v203, v219, v203
	v_add_f32_e32 v203, v222, v203
	ds_read_b128 v[172:175], v194 offset:32768
	ds_read_b128 v[228:231], v194 offset:40960
	s_waitcnt lgkmcnt(1)
	v_mfma_f32_32x32x16_bf16 v[82:97], v[172:175], v[124:127], v[82:97]
	v_add_f32_e32 v203, v208, v203
	v_add_f32_e32 v203, v198, v203
	v_add_f32_e32 v203, v201, v203
	v_add_f32_e32 v203, v209, v203
	s_waitcnt lgkmcnt(0)
	v_mfma_f32_32x32x16_bf16 v[66:81], v[228:231], v[124:127], v[66:81]
	v_add_f32_e32 v203, v214, v203
	v_add_f32_e32 v203, v205, v203
	v_add_f32_e32 v203, v206, v203
	v_add_f32_e32 v203, v207, v203
	ds_read_b128 v[172:175], v195 offset:32768
	ds_read_b128 v[228:231], v195 offset:40960
	s_waitcnt lgkmcnt(1)
	v_mfma_f32_32x32x16_bf16 v[82:97], v[172:175], v[120:123], v[82:97]
	v_add_f32_e32 v203, v181, v203
	v_add_f32_e32 v203, v215, v203
	v_add_f32_e32 v203, v216, v203
	v_add_f32_e32 v203, v180, v203
	s_waitcnt lgkmcnt(0)
	v_mfma_f32_32x32x16_bf16 v[66:81], v[228:231], v[120:123], v[66:81]
	v_mov_b32_e32 v204, v203
	v_cvt_pk_bf16_f32 v148, v148, v163
	v_cvt_pk_bf16_f32 v149, v149, v162
	v_cvt_pk_bf16_f32 v150, v150, v161
	ds_read_b128 v[172:175], v169 offset:32896
	ds_read_b128 v[228:231], v169 offset:41088
	s_waitcnt lgkmcnt(1)
	v_mfma_f32_32x32x16_bf16 v[82:97], v[172:175], v[116:119], v[82:97]
	v_cvt_pk_bf16_f32 v151, v151, v160
	v_cvt_pk_bf16_f32 v152, v152, v159
	v_cvt_pk_bf16_f32 v153, v153, v158
	v_cvt_pk_bf16_f32 v154, v154, v157
	s_waitcnt lgkmcnt(0)
	v_mfma_f32_32x32x16_bf16 v[66:81], v[228:231], v[116:119], v[66:81]
	v_cvt_pk_bf16_f32 v155, v155, v156
	v_cvt_pk_bf16_f32 v156, v217, v218
	v_cvt_pk_bf16_f32 v157, v219, v222
	ds_read_b128 v[172:175], v193 offset:32896
	ds_read_b128 v[228:231], v193 offset:41088
	s_waitcnt lgkmcnt(1)
	v_mfma_f32_32x32x16_bf16 v[82:97], v[172:175], v[112:115], v[82:97]
	v_cvt_pk_bf16_f32 v158, v208, v198
	v_cvt_pk_bf16_f32 v159, v201, v209
	v_cvt_pk_bf16_f32 v160, v214, v205
	s_waitcnt lgkmcnt(0)
	v_mfma_f32_32x32x16_bf16 v[66:81], v[228:231], v[112:115], v[66:81]
	v_cvt_pk_bf16_f32 v161, v206, v207
	v_cvt_pk_bf16_f32 v162, v181, v215
	v_cvt_pk_bf16_f32 v163, v216, v180
	ds_read_b128 v[172:175], v194 offset:32896
	ds_read_b128 v[228:231], v194 offset:41088
	s_waitcnt lgkmcnt(1)
	v_mfma_f32_32x32x16_bf16 v[82:97], v[172:175], v[108:111], v[82:97]
	s_nop 1
	v_permlane32_swap_b32_e32 v203, v204
	v_permlane32_swap_b32_e32 v148, v150
	v_permlane32_swap_b32_e32 v149, v151
	s_waitcnt lgkmcnt(0)
	v_mfma_f32_32x32x16_bf16 v[66:81], v[228:231], v[108:111], v[66:81]
	v_permlane32_swap_b32_e32 v152, v154
	v_permlane32_swap_b32_e32 v153, v155
	v_permlane32_swap_b32_e32 v156, v158
	ds_read_b128 v[172:175], v195 offset:32896
	ds_read_b128 v[228:231], v195 offset:41088
	ds_read_b64_tr_b16 v[206:207], v185 offset:0x5000
	ds_read_b64_tr_b16 v[208:209], v185 offset:0x5800
	ds_read_b64_tr_b16 v[224:225], v185 offset:0x6000
	ds_read_b64_tr_b16 v[226:227], v185 offset:0x6800
	s_waitcnt lgkmcnt(5)
	v_mfma_f32_32x32x16_bf16 v[82:97], v[172:175], v[104:107], v[82:97]
	v_permlane32_swap_b32_e32 v157, v159
	v_permlane32_swap_b32_e32 v160, v162
	v_permlane32_swap_b32_e32 v161, v163
	s_waitcnt lgkmcnt(4)
	v_mfma_f32_32x32x16_bf16 v[66:81], v[228:231], v[104:107], v[66:81]
	ds_read_b64_tr_b16 v[172:173], v185 offset:0x4000
	ds_read_b64_tr_b16 v[174:175], v185 offset:0x4800
	ds_read_b64_tr_b16 v[228:229], v185 offset:0x7000
	ds_read_b64_tr_b16 v[230:231], v185 offset:0x7800
	s_cmp_lt_u32 s3, s2
	s_cselect_b64 s[22:23], -1, 0
	s_cmp_ge_u32 s3, s2
	s_cbranch_scc1 .LBB0_97
	s_mov_b32 s100, 1

; #define SBAR() __builtin_amdgcn_sched_barrier(0)
; #define SLOAD_H(Kp, Vp, k0) do { S.st_v0 = load8(ROW(Vp, k0, sr)); S.st_v1 = load8(ROW(Vp, k0, 32 + sr));              \
;                          S.st_k0 = load8(ROW(Kp, k0, sr)); S.st_k1 = load8(ROW(Kp, k0, 32 + sr)); } while (0)
; __device__ __forceinline__ void moba_block(const BlockRef& cur, const BlockRef& nxt, char* lds, Seam& S) {
;     ...
;     for (int t = 1; t + 1 < NT; t += 2) {
;         HALF_STEP(pB0, pB1, mnB, alB, pA0, pA1, alA, t, 1, 0, 0);
;         HALF_STEP(pA0, pA1, mnA, alA, pB0, pB1, alB, t + 1, 0, 1, 1);
;     }
;     const bool even = (NT & 1) == 0;
;     if (even) { SBAR(); qkt<1>(pB0, pB1, K_lds, r32, hi, S.qr); SBAR(); }
;     SLOAD_H(nxt.K, nxt.V, 0); SBAR();
.LBB0_107:
	s_cmp_eq_u32 s100, 0
	s_cbranch_scc1 .Lmy_exit_nov
	s_lshl_b32 m0, s32, 1
	s_sub_i32 m0, m0, 0xc000
	s_nop 0
	global_load_lds_dwordx4 v[248:249], off
	s_add_i32 m0, m0, 896
	s_nop 0
	global_load_lds_dwordx4 v[248:249], off offset:128
